# gated-DeltaNet: lower(QK^T) per chunk precomputed (f32 MFMA) with Minv, K Q^T chain and its exchange dropped from the recurrence; chunk preparation interleaved between the MFMAs
# speedup vs baseline: 1.0177x; 1.0102x over previous
; __device__ __forceinline__ int otid() { int t = threadIdx.x; asm volatile("" : "+v"(t)); return t; }
; __device__ __forceinline__ void gdn_item(const Params& p, int item, float* sm) {
;   const int b = item >> 5, h = (item >> 3) & 3, c0 = (item & 7) * 16;
;   const bf16_t* gp = (const bf16_t*)p.out;
;   const float* gg = (const float*)(p.ws + OFF_GG);
;   bf16_t* O = (bf16_t*)(p.ws + OFF_O);
;   constexpr int TC = 16;
;   constexpr int BUF = 2 * TC * 128 + TC * 16 + 2 * TC + TC * 16 + TC;
;   const int tid = otid(), lane = tid & 63, wave = tid >> 6;
;   const int sub = lane & 15, cw = wave * 4 + (lane >> 4);
;   const int ltt = tid >> 4, lseg = tid & 15;
;   float S[8];
; #pragma unroll
;   for (int i = 0; i < 8; i++) S[i] = 0.f;
;   const size_t rowb = (size_t)b * LP;
;   uint4 pq, pk; bf16_t pv; float pg = 0.f, pb = 0.f;
;     ...
;   __syncthreads();
;   GDN_LOAD(PADR)
;   GDN_STORE(0)
;   __syncthreads();
.Lgd_item:
	s_setprio 3
	v_readlane_b32 s14, v244, 27
	v_readlane_b32 s8, v247, 3
	v_readlane_b32 s9, v247, 4
	v_readlane_b32 s4, v247, 1
	v_readlane_b32 s5, v247, 2
	v_and_b32_e32 v136, 15, v2
	v_lshrrev_b32_e32 v137, 4, v2
	v_bfe_u32 v138, v2, 4, 2
	v_lshrrev_b32_e32 v139, 6, v2
	s_lshr_b32 s10, s14, 5
	s_bfe_u32 s11, s14, 0x20003
	s_and_b32 s12, s14, 7
	s_lshl_b32 s12, s12, 5
	s_mul_i32 s13, s10, 0x2080
	s_add_i32 s13, s13, 0x70
	s_add_u32 s6, s8, 0x19c8c000
	s_addc_u32 s7, s9, 0
	s_add_u32 s8, s8, 0x19d90000
	s_addc_u32 s9, s9, 0
	s_lshl_b32 s14, s10, 2
	s_add_i32 s14, s14, s11
	s_mul_i32 s14, s14, 0x80400
	s_add_u32 s10, s4, 0x71a0000
	s_addc_u32 s15, s5, 0
	s_add_u32 s10, s10, s14
	s_addc_u32 s11, s15, 0
	v_readfirstlane_b32 s100, v139
	v_lshlrev_b32_e32 v151, 9, v136
	v_lshl_add_u32 v151, v139, 7, v151
	v_lshl_add_u32 v151, v138, 4, v151
	v_lshlrev_b32_e32 v152, 11, v138
	v_lshl_add_u32 v152, v139, 7, v152
	v_lshl_add_u32 v152, v136, 2, v152
	v_lshlrev_b32_e32 v153, 6, v136
	v_lshl_add_u32 v153, v138, 4, v153
	v_lshlrev_b32_e32 v154, 4, v138
	v_and_b32_e32 v140, 63, v2
	v_lshlrev_b32_e32 v156, 4, v140
	v_add_u32_e32 v156, 0x8a00, v156
	s_mul_i32 s101, s100, 0xc00
	v_add_u32_e32 v155, s101, v156
	v_lshlrev_b32_e32 v157, 5, v2
	v_lshl_add_u32 v158, v136, 4, v137
	v_lshlrev_b32_e32 v158, 2, v158
	v_add_u32_e32 v158, 16384, v158
	v_lshlrev_b32_e32 v159, 2, v136
	v_lshlrev_b32_e32 v141, 2, v138
	v_add_u32_e32 v142, 0, v141
	v_cmp_le_u32_e32 vcc, v142, v136
	s_nop 1
	v_cndmask_b32_e64 v166, 0, 1.0, vcc
	v_add_u32_e32 v142, 1, v141
	v_cmp_le_u32_e32 vcc, v142, v136
	s_nop 1
	v_cndmask_b32_e64 v167, 0, 1.0, vcc
	v_add_u32_e32 v142, 2, v141
	v_cmp_le_u32_e32 vcc, v142, v136
	s_nop 1
	v_cndmask_b32_e64 v168, 0, 1.0, vcc
	v_add_u32_e32 v142, 3, v141
	v_cmp_le_u32_e32 vcc, v142, v136
	s_nop 1
	v_cndmask_b32_e64 v169, 0, 1.0, vcc
	v_readlane_b32 s101, v244, 27
	s_bfe_u32 s101, s101, 0x20003
	v_add_u32_e32 v142, s13, v137
	s_lshl_b32 s14, s101, 8
	v_lshl_add_u32 v143, v136, 4, s14
	s_movk_i32 s15, 0xc00
	v_mad_u32_u24 v118, v142, s15, v143
	s_add_i32 s14, s14, s12
	v_lshl_add_u32 v143, v136, 1, s14
	v_mad_u32_u24 v119, v142, s15, v143
	v_add_u32_e32 v119, 0x800, v119
	v_add_u32_e32 v142, s13, v136
	s_lshl_b32 s15, s101, 2
	v_lshl_add_u32 v140, v142, 5, s15
	v_add_u32_e32 v142, s13, v141
	v_lshl_add_u32 v57, v142, 11, v143
	v_add_u32_e32 v57, 0x400, v57
	v_add_u32_e32 v58, 0x1000, v57
	v_lshlrev_b32_e32 v59, 6, v136
	v_lshl_add_u32 v59, v138, 4, v59
	v_readlane_b32 s14, v244, 27
	s_lshr_b32 s14, s14, 3
	s_mul_i32 s12, s14, 0x80400
	v_readlane_b32 s14, v247, 3
	v_readlane_b32 s15, v247, 4
	s_add_u32 s14, s14, 0xac40000
	s_addc_u32 s15, s15, 0
	s_add_u32 s14, s14, s12
	s_addc_u32 s15, s15, 0
	v_mov_b32_e32 v12, 0
	v_mov_b32_e32 v13, 0
	v_mov_b32_e32 v14, 0
	v_mov_b32_e32 v15, 0
	v_mov_b32_e32 v16, 0
	v_mov_b32_e32 v17, 0
	v_mov_b32_e32 v18, 0
	v_mov_b32_e32 v19, 0
	s_barrier
	global_load_dwordx4 v[108:111], v118, s[4:5]
	global_load_dwordx4 v[112:115], v118, s[4:5] offset:1024
	global_load_ushort v116, v119, s[4:5]
	global_load_dword v117, v140, s[6:7]
	s_add_u32 s4, s4, 0xc000
	s_addc_u32 s5, s5, 0
	s_add_u32 s6, s6, 0x200
	s_addc_u32 s7, s7, 0
	global_load_dwordx4 v[88:91], v59, s[10:11]
	s_add_u32 s10, s10, 0x400
	s_addc_u32 s11, s11, 0
	global_load_dwordx4 v[92:95], v59, s[14:15]
	s_add_u32 s14, s14, 0x400
	s_addc_u32 s15, s15, 0
	v_mov_b32_e32 v148, v157
	v_mov_b32_e32 v149, v158
	v_mov_b32_e32 v150, v159
	s_waitcnt vmcnt(0)
	v_lshlrev_b32_e32 v120, 16, v108
	v_and_b32_e32 v121, 0xffff0000, v108
	v_lshlrev_b32_e32 v122, 16, v109
	v_and_b32_e32 v123, 0xffff0000, v109
	v_lshlrev_b32_e32 v124, 16, v110
	v_and_b32_e32 v125, 0xffff0000, v110
	v_lshlrev_b32_e32 v126, 16, v111
	v_and_b32_e32 v127, 0xffff0000, v111
	v_lshlrev_b32_e32 v128, 16, v112
	v_and_b32_e32 v129, 0xffff0000, v112
	v_lshlrev_b32_e32 v130, 16, v113
	v_and_b32_e32 v131, 0xffff0000, v113
	v_lshlrev_b32_e32 v132, 16, v114
	v_and_b32_e32 v133, 0xffff0000, v114
	v_lshlrev_b32_e32 v134, 16, v115
	v_and_b32_e32 v135, 0xffff0000, v115
	v_mov_b32_e32 v136, v117
	v_lshlrev_b32_e32 v137, 16, v116
	s_nop 0
	v_add_f32_dpp v136, v136, v136 row_shr:1 row_mask:0xf bank_mask:0xf bound_ctrl:1
	s_nop 1
	v_add_f32_dpp v136, v136, v136 row_shr:2 row_mask:0xf bank_mask:0xf bound_ctrl:1
	s_nop 1
	v_add_f32_dpp v136, v136, v136 row_shr:4 row_mask:0xf bank_mask:0xf bound_ctrl:1
	s_nop 1
	v_add_f32_dpp v136, v136, v136 row_shr:8 row_mask:0xf bank_mask:0xf bound_ctrl:1
	s_nop 0
	v_max_f32_e32 v136, 0xc2a00000, v136
	v_mul_f32_e32 v136, 0x3fb8aa3b, v136
	v_exp_f32_e32 v138, v136
	v_exp_f32_e64 v139, -v136
	s_nop 0
	v_mul_f32_e32 v136, 0x3db504f3, v138
	ds_write_b128 v148, v[120:123]
	ds_write_b128 v148, v[124:127] offset:16
	ds_write_b128 v148, v[128:131] offset:8192
	ds_write_b128 v148, v[132:135] offset:8208
	ds_write_b32 v149, v137
	ds_write_b32 v150, v139 offset:17408
	ds_write_b32 v150, v138 offset:17536
	ds_write_b32 v150, v136 offset:17472
	global_load_dwordx4 v[108:111], v118, s[4:5]
	global_load_dwordx4 v[112:115], v118, s[4:5] offset:1024
	global_load_ushort v116, v119, s[4:5]
	global_load_dword v117, v140, s[6:7]
	s_add_u32 s4, s4, 0xc000
	s_addc_u32 s5, s5, 0
	s_add_u32 s6, s6, 0x200
	s_addc_u32 s7, s7, 0
	s_mov_b32 s0, 0
	s_mov_b32 s1, 0
	s_waitcnt lgkmcnt(0)
	s_barrier
; __device__ __forceinline__ void gdn_item(const Params& p, int item, float* sm) {
;     ...
;   for (int ch = 0; ch < NCH; ch++) {
;     const int bi = ch & 1;
;     const int t0 = PADR + ch * TC;
;     if (ch + 1 < NCH) GDN_LOAD(t0 + TC)
;     {
;       const float* bq = sm + bi * BUF;
;       const float* bk = bq + TC * 128;
;       const float* bv = bq + 2 * TC * 128;
;       const float* bg = bv + TC * 16;
;       float* bo = sm + bi * BUF + 2 * TC * 128 + TC * 16 + 2 * TC;
;       float oreg[TC];
; #pragma unroll
;       for (int t = 0; t < TC; t++) {
;         const float4 k0 = *(const float4*)(bk + t * 128 + sub * 4);
;         const float4 k1 = *(const float4*)(bk + t * 128 + 64 + sub * 4);
;         const float4 q0 = *(const float4*)(bq + t * 128 + sub * 4);
;         const float4 q1 = *(const float4*)(bq + t * 128 + 64 + sub * 4);
;         const float v = bv[t * 16 + cw];
;         const float g = bg[t], be = bg[TC + t];
;         const float qk = bo[TC * 16 + t];
;         float pa = k0.x * S[0] + k0.y * S[1];
;         float pb2 = k0.z * S[2] + k0.w * S[3];
;         float qa = q0.x * S[0] + q0.y * S[1];
;         float qb2 = q0.z * S[2] + q0.w * S[3];
;         pa += k1.x * S[4] + k1.y * S[5];
;         pb2 += k1.z * S[6] + k1.w * S[7];
;         qa += q1.x * S[4] + q1.y * S[5];
;         qb2 += q1.z * S[6] + q1.w * S[7];
;         const float ks = dpp_sum16(pa + pb2);
;         const float qs = dpp_sum16(qa + qb2);
;         const float coef = be * (v - g * ks);
;         const float oo = g * qs + coef * qk;
;         S[0] = g * S[0] + coef * k0.x; S[1] = g * S[1] + coef * k0.y; S[2] = g * S[2] + coef * k0.z; S[3] = g * S[3] + coef * k0.w;
;         S[4] = g * S[4] + coef * k1.x; S[5] = g * S[5] + coef * k1.y; S[6] = g * S[6] + coef * k1.z; S[7] = g * S[7] + coef * k1.w;
;         oreg[t] = oo * 0.08838834764831845f;
.Lgd_chunk:
	v_add_u32_e32 v141, s1, v151
	v_add_u32_e32 v142, s1, v152
	v_add_u32_e32 v143, s1, v153
	v_add_u32_e32 v144, s1, v154
	v_mov_b32_e32 v145, s1
	s_xor_b32 s2, s1, 0x4500
	s_and_b32 s12, s0, 1
	s_mul_i32 s12, s12, 0x3000
	v_add_u32_e32 v146, s12, v155
	v_add_u32_e32 v147, s12, v156
	ds_read_b128 v[20:23], v141 offset:8192
	ds_read_b128 v[28:31], v141 offset:0
	ds_read_b128 v[24:27], v141 offset:8256
	ds_read_b128 v[32:35], v141 offset:64
	v_add_u32_e32 v148, s2, v157
	v_add_u32_e32 v149, s2, v158
	v_add_u32_e32 v150, s2, v159
	s_waitcnt lgkmcnt(0)
	v_mfma_f32_16x16x4_f32 v[60:63], v20, v12, 0
	ds_read_b32 v36, v142 offset:8192
	v_mfma_f32_16x16x4_f32 v[64:67], v28, v12, 0
	ds_read_b32 v37, v142 offset:8704
	v_mfma_f32_16x16x4_f32 v[60:63], v21, v13, v[60:63]
	ds_read_b32 v38, v142 offset:9216
	v_mfma_f32_16x16x4_f32 v[64:67], v29, v13, v[64:67]
	ds_read_b32 v39, v142 offset:9728
	s_waitcnt vmcnt(0)
	v_lshlrev_b32_e32 v120, 16, v108
	v_and_b32_e32 v121, 0xffff0000, v108
	v_lshlrev_b32_e32 v122, 16, v109
	v_mfma_f32_16x16x4_f32 v[60:63], v22, v14, v[60:63]
	ds_read_b32 v40, v142 offset:8256
	v_and_b32_e32 v123, 0xffff0000, v109
	v_lshlrev_b32_e32 v124, 16, v110
	v_and_b32_e32 v125, 0xffff0000, v110
	v_mfma_f32_16x16x4_f32 v[64:67], v30, v14, v[64:67]
	ds_read_b32 v41, v142 offset:8768
	v_lshlrev_b32_e32 v126, 16, v111
	v_and_b32_e32 v127, 0xffff0000, v111
	v_lshlrev_b32_e32 v128, 16, v112
	v_and_b32_e32 v129, 0xffff0000, v112
	v_mfma_f32_16x16x4_f32 v[60:63], v23, v15, v[60:63]
	ds_read_b32 v42, v142 offset:9280
	v_lshlrev_b32_e32 v130, 16, v113
	v_and_b32_e32 v131, 0xffff0000, v113
	v_lshlrev_b32_e32 v132, 16, v114
	v_mfma_f32_16x16x4_f32 v[64:67], v31, v15, v[64:67]
	ds_read_b32 v43, v142 offset:9792
	v_and_b32_e32 v133, 0xffff0000, v114
	v_lshlrev_b32_e32 v134, 16, v115
	v_and_b32_e32 v135, 0xffff0000, v115
	v_mov_b32_e32 v136, v117
	v_mfma_f32_16x16x4_f32 v[60:63], v24, v16, v[60:63]
	ds_read_b128 v[44:47], v143 offset:16384
	v_lshlrev_b32_e32 v137, 16, v116
	s_nop 0
	v_add_f32_dpp v136, v136, v136 row_shr:1 row_mask:0xf bank_mask:0xf bound_ctrl:1
	v_mfma_f32_16x16x4_f32 v[64:67], v32, v16, v[64:67]
	ds_read_b128 v[48:51], v144 offset:17408
	s_nop 1
	v_add_f32_dpp v136, v136, v136 row_shr:2 row_mask:0xf bank_mask:0xf bound_ctrl:1
	s_nop 1
	v_add_f32_dpp v136, v136, v136 row_shr:4 row_mask:0xf bank_mask:0xf bound_ctrl:1
	v_mfma_f32_16x16x4_f32 v[60:63], v25, v17, v[60:63]
	ds_read_b128 v[52:55], v144 offset:17472
	s_nop 1
	v_add_f32_dpp v136, v136, v136 row_shr:8 row_mask:0xf bank_mask:0xf bound_ctrl:1
	s_nop 0
	v_mfma_f32_16x16x4_f32 v[64:67], v33, v17, v[64:67]
	ds_read_b32 v56, v145 offset:17596
	v_max_f32_e32 v136, 0xc2a00000, v136
	v_mul_f32_e32 v136, 0x3fb8aa3b, v136
	v_exp_f32_e32 v138, v136
	v_exp_f32_e64 v139, -v136
	v_mfma_f32_16x16x4_f32 v[60:63], v26, v18, v[60:63]
	s_nop 0
	v_mul_f32_e32 v136, 0x3db504f3, v138
	ds_write_b128 v148, v[120:123]
	v_mfma_f32_16x16x4_f32 v[64:67], v34, v18, v[64:67]
	ds_write_b128 v148, v[124:127] offset:16
	ds_write_b128 v148, v[128:131] offset:8192
	ds_write_b128 v148, v[132:135] offset:8208
	ds_write_b32 v149, v137
	v_mfma_f32_16x16x4_f32 v[60:63], v27, v19, v[60:63]
	ds_write_b32 v150, v139 offset:17408
	ds_write_b32 v150, v138 offset:17536
	ds_write_b32 v150, v136 offset:17472
	v_mfma_f32_16x16x4_f32 v[64:67], v35, v19, v[64:67]
	global_load_dwordx4 v[108:111], v118, s[4:5]
	global_load_dwordx4 v[112:115], v118, s[4:5] offset:1024
	global_load_ushort v116, v119, s[4:5]
	global_load_dword v117, v140, s[6:7]
	s_cmp_lt_u32 s0, 0x1fe
	s_cselect_b32 s12, 0xc000, 0
	s_cselect_b32 s101, 0x200, 0
	s_add_u32 s4, s4, s12
	s_addc_u32 s5, s5, 0
	s_add_u32 s6, s6, s101
	s_addc_u32 s7, s7, 0
	s_nop 3
	ds_write_b128 v146, v[60:63]
	ds_write_b128 v146, v[64:67] offset:1024
	s_waitcnt lgkmcnt(0)
	s_barrier
	ds_read_b128 v[72:75], v147 offset:0
	ds_read_b128 v[76:79], v147 offset:3072
	ds_read_b128 v[80:83], v147 offset:6144
	ds_read_b128 v[84:87], v147 offset:9216
	s_waitcnt lgkmcnt(0)
	v_add_f32_e32 v72, v72, v76
	v_add_f32_e32 v80, v80, v84
	v_add_f32_e32 v73, v73, v77
	v_add_f32_e32 v81, v81, v85
	v_add_f32_e32 v74, v74, v78
	v_add_f32_e32 v82, v82, v86
	v_add_f32_e32 v75, v75, v79
	v_add_f32_e32 v83, v83, v87
	v_add_f32_e32 v72, v72, v80
	v_add_f32_e32 v73, v73, v81
	v_add_f32_e32 v74, v74, v82
	v_add_f32_e32 v75, v75, v83
	v_fma_f32 v96, v44, v48, -v72
	v_fma_f32 v97, v45, v49, -v73
	v_fma_f32 v98, v46, v50, -v74
	v_fma_f32 v99, v47, v51, -v75
	s_nop 1
	v_mfma_f32_16x16x4_f32 v[100:103], v88, v96, 0
	v_mfma_f32_16x16x4_f32 v[100:103], v89, v97, v[100:103]
	v_mfma_f32_16x16x4_f32 v[100:103], v90, v98, v[100:103]
	v_mfma_f32_16x16x4_f32 v[100:103], v91, v99, v[100:103]
	global_load_dwordx4 v[88:91], v59, s[10:11]
	s_cmp_lt_u32 s0, 0x1ff
	s_cselect_b32 s12, 0x400, 0
	s_add_u32 s10, s10, s12
	s_addc_u32 s11, s11, 0
	s_and_b32 s12, s0, 3
	s_cmp_eq_u32 s12, s100
	s_cbranch_scc0 .Lgd_upd
	ds_read_b128 v[72:75], v147 offset:1024
	ds_read_b128 v[76:79], v147 offset:4096
	ds_read_b128 v[80:83], v147 offset:7168
	ds_read_b128 v[84:87], v147 offset:10240
	s_waitcnt lgkmcnt(0)
	v_add_f32_e32 v72, v72, v76
	v_add_f32_e32 v80, v80, v84
	v_add_f32_e32 v73, v73, v77
	v_add_f32_e32 v81, v81, v85
	v_add_f32_e32 v74, v74, v78
	v_add_f32_e32 v82, v82, v86
	v_add_f32_e32 v75, v75, v79
	v_add_f32_e32 v83, v83, v87
	v_add_f32_e32 v104, v72, v80
	v_add_f32_e32 v105, v73, v81
	v_add_f32_e32 v106, v74, v82
	v_add_f32_e32 v107, v75, v83
	s_nop 7
	s_nop 1
	v_mfma_f32_16x16x4_f32 v[104:107], v92, v100, v[104:107]
	v_mfma_f32_16x16x4_f32 v[104:107], v93, v101, v[104:107]
	v_mfma_f32_16x16x4_f32 v[104:107], v94, v102, v[104:107]
	v_mfma_f32_16x16x4_f32 v[104:107], v95, v103, v[104:107]
; __device__ __forceinline__ void gdn_item(const Params& p, int item, float* sm) {
;     ...
;         const float ks = dpp_sum16(pa + pb2);
;         const float qs = dpp_sum16(qa + qb2);
;         const float coef = be * (v - g * ks);
;         const float oo = g * qs + coef * qk;
;         S[0] = g * S[0] + coef * k0.x; S[1] = g * S[1] + coef * k0.y; S[2] = g * S[2] + coef * k0.z; S[3] = g * S[3] + coef * k0.w;
;         S[4] = g * S[4] + coef * k1.x; S[5] = g * S[5] + coef * k1.y; S[6] = g * S[6] + coef * k1.z; S[7] = g * S[7] + coef * k1.w;
;         oreg[t] = oo * 0.08838834764831845f;
;       }
;       if (sub == 0) {
; #pragma unroll
;         for (int t = 0; t < TC; t++) bo[t * 16 + cw] = oreg[t];
;       }
;     }
;     if (ch + 1 < NCH) GDN_STORE(bi ^ 1)
;     __syncthreads();
;     {
;       const float ov = sm[bi * BUF + 2 * TC * 128 + TC * 16 + 2 * TC + ltt * 16 + lseg];
;       O[(rowb + t0 + ltt) * D + 512 + h * 128 + c0 + lseg] = f2bf(ov);
.Lgd_upd:
	global_load_dwordx4 v[92:95], v59, s[14:15]
	s_cmp_lt_u32 s0, 0x1ff
	s_cselect_b32 s101, 0x400, 0
	s_add_u32 s14, s14, s101
	s_addc_u32 s15, s15, 0
	s_nop 5
	v_mfma_f32_16x16x4_f32 v[12:15], v36, v100, v[12:15]
	v_mfma_f32_16x16x4_f32 v[16:19], v40, v100, v[16:19]
	v_mfma_f32_16x16x4_f32 v[12:15], v37, v101, v[12:15]
	v_mfma_f32_16x16x4_f32 v[16:19], v41, v101, v[16:19]
	v_mfma_f32_16x16x4_f32 v[12:15], v38, v102, v[12:15]
	v_mfma_f32_16x16x4_f32 v[16:19], v42, v102, v[16:19]
	v_mfma_f32_16x16x4_f32 v[12:15], v39, v103, v[12:15]
	v_mfma_f32_16x16x4_f32 v[16:19], v43, v103, v[16:19]
	s_cmp_eq_u32 s12, s100
	s_cbranch_scc0 .Lgd_noout
	s_nop 7
	s_nop 3
	v_mul_f32_e32 v104, v104, v52
	v_mul_f32_e32 v105, v105, v53
	v_mul_f32_e32 v106, v106, v54
	v_mul_f32_e32 v107, v107, v55
	v_cvt_pk_bf16_f32 v104, v104, v104
	v_cvt_pk_bf16_f32 v105, v105, v105
	v_cvt_pk_bf16_f32 v106, v106, v106
	v_cvt_pk_bf16_f32 v107, v107, v107
	global_store_short v57, v104, s[8:9]
	global_store_short v57, v105, s[8:9] offset:2048
	global_store_short v58, v106, s[8:9]
	global_store_short v58, v107, s[8:9] offset:2048
.Lgd_noout:
	s_add_u32 s8, s8, 0x8000
	s_addc_u32 s9, s9, 0
	s_nop 6
	v_mul_f32_e32 v12, v12, v56
	v_mul_f32_e32 v13, v13, v56
	v_mul_f32_e32 v14, v14, v56
	v_mul_f32_e32 v15, v15, v56
	v_mul_f32_e32 v16, v16, v56
	v_mul_f32_e32 v17, v17, v56
	v_mul_f32_e32 v18, v18, v56
	v_mul_f32_e32 v19, v19, v56
	s_mov_b32 s1, s2
	s_add_i32 s0, s0, 1
	s_cmp_lg_u32 s0, 513
	s_cbranch_scc1 .Lgd_chunk
	s_waitcnt vmcnt(0) lgkmcnt(0)
	s_setprio 0

.LBB0_2962:
	s_waitcnt lgkmcnt(0)
	v_readfirstlane_b32 s0, v243
	s_cmp_eq_u32 s24, 5
	s_cbranch_scc0 .Lmv_skip
	s_cmp_eq_u32 s0, 1
	s_cbranch_scc1 .Lmv_skip
	v_readlane_b32 s2, v244, 27
	v_readlane_b32 s4, v247, 1
	v_readlane_b32 s5, v247, 2
	v_readlane_b32 s6, v247, 3
	v_readlane_b32 s7, v247, 4
	v_lshrrev_b32_e32 v156, 6, v2
	v_and_b32_e32 v157, 63, v2
	s_add_u32 s8, s4, 0x71a0000
	s_addc_u32 s9, s5, 0
	v_readfirstlane_b32 s10, v156
	v_and_b32_e32 v152, 15, v157
	v_lshrrev_b32_e32 v158, 4, v157
	s_lshl_b32 s2, s2, 2
	s_add_i32 s2, s2, s10
	v_readlane_b32 s11, v247, 0
	s_lshl_b32 s11, s11, 2
	s_lshl_b32 s12, s10, 11
	v_mul_u32_u24_e32 v153, 0xc00, v152
	v_lshl_add_u32 v153, v158, 6, v153
	v_lshlrev_b32_e32 v154, 5, v152
	v_lshlrev_b32_e32 v155, 6, v152
	v_lshl_add_u32 v155, v158, 4, v155
	v_add_u32_e32 v155, s12, v155
	v_lshlrev_b32_e32 v160, 2, v158
	v_lshlrev_b32_e32 v242, 2, v152
	v_lshl_add_u32 v242, v158, 8, v242
.Lmv_item:
	s_cmp_ge_u32 s2, 0x2010
	s_cbranch_scc1 .Lmv_done
	s_mul_hi_u32 s13, s2, 0x7fc020
	s_mul_i32 s14, s13, 0x201
	s_sub_u32 s14, s2, s14
	s_lshr_b32 s15, s13, 2
	s_and_b32 s16, s13, 3
	s_mul_i32 s17, s15, 0x2080
	s_lshl_b32 s18, s14, 4
	s_add_i32 s17, s17, s18
	s_add_i32 s17, s17, 0x70
	s_mul_i32 s18, s17, 0xc00
	s_lshl_b32 s19, s16, 8
	s_add_i32 s18, s18, s19
	s_add_i32 s18, s18, 0x400
	v_add_u32_e32 v156, s18, v153
	s_lshl_b32 s19, s17, 5
	s_lshl_b32 s20, s16, 2
	s_add_i32 s19, s19, s20
	s_add_i32 s19, s19, 0x19c8c010
	v_add_u32_e32 v157, s19, v154
	global_load_dwordx4 v[64:67], v156, s[4:5]
	global_load_dwordx4 v[68:71], v156, s[4:5] offset:16
	global_load_dwordx4 v[72:75], v156, s[4:5] offset:32
	global_load_dwordx4 v[76:79], v156, s[4:5] offset:48
	global_load_dword v158, v157, s[6:7]
	v_add_u32_e32 v156, 0xfffffc00, v156
	global_load_dwordx4 v[226:229], v156, s[4:5]
	global_load_dwordx4 v[230:233], v156, s[4:5] offset:16
	global_load_dwordx4 v[234:237], v156, s[4:5] offset:32
	global_load_dwordx4 v[238:241], v156, s[4:5] offset:48
	s_waitcnt vmcnt(4)
	v_lshlrev_b32_e32 v32, 16, v64
	v_and_b32_e32 v33, 0xffff0000, v64
	v_lshlrev_b32_e32 v34, 16, v65
	v_and_b32_e32 v35, 0xffff0000, v65
	v_lshlrev_b32_e32 v36, 16, v66
	v_and_b32_e32 v37, 0xffff0000, v66
	v_lshlrev_b32_e32 v38, 16, v67
	v_and_b32_e32 v39, 0xffff0000, v67
	v_lshlrev_b32_e32 v40, 16, v68
	v_and_b32_e32 v41, 0xffff0000, v68
	v_lshlrev_b32_e32 v42, 16, v69
	v_and_b32_e32 v43, 0xffff0000, v69
	v_lshlrev_b32_e32 v44, 16, v70
	v_and_b32_e32 v45, 0xffff0000, v70
	v_lshlrev_b32_e32 v46, 16, v71
	v_and_b32_e32 v47, 0xffff0000, v71
	v_lshlrev_b32_e32 v48, 16, v72
	v_and_b32_e32 v49, 0xffff0000, v72
	v_lshlrev_b32_e32 v50, 16, v73
	v_and_b32_e32 v51, 0xffff0000, v73
	v_lshlrev_b32_e32 v52, 16, v74
	v_and_b32_e32 v53, 0xffff0000, v74
	v_lshlrev_b32_e32 v54, 16, v75
	v_and_b32_e32 v55, 0xffff0000, v75
	v_lshlrev_b32_e32 v56, 16, v76
	v_and_b32_e32 v57, 0xffff0000, v76
	v_lshlrev_b32_e32 v58, 16, v77
	v_and_b32_e32 v59, 0xffff0000, v77
	v_lshlrev_b32_e32 v60, 16, v78
	v_and_b32_e32 v61, 0xffff0000, v78
	v_lshlrev_b32_e32 v62, 16, v79
	v_and_b32_e32 v63, 0xffff0000, v79
	v_lshl_add_u32 v156, v152, 2, s12
	ds_write_b32 v156, v158 offset:1024
	v_mfma_f32_16x16x4_f32 v[80:83], v32, v32, 0
	v_mfma_f32_16x16x4_f32 v[84:87], v33, v33, 0
	v_mfma_f32_16x16x4_f32 v[80:83], v34, v34, v[80:83]
	v_mfma_f32_16x16x4_f32 v[84:87], v35, v35, v[84:87]
	v_mfma_f32_16x16x4_f32 v[80:83], v36, v36, v[80:83]
	v_mfma_f32_16x16x4_f32 v[84:87], v37, v37, v[84:87]
	v_mfma_f32_16x16x4_f32 v[80:83], v38, v38, v[80:83]
	v_mfma_f32_16x16x4_f32 v[84:87], v39, v39, v[84:87]
	v_mfma_f32_16x16x4_f32 v[80:83], v40, v40, v[80:83]
	v_mfma_f32_16x16x4_f32 v[84:87], v41, v41, v[84:87]
	v_mfma_f32_16x16x4_f32 v[80:83], v42, v42, v[80:83]
	v_mfma_f32_16x16x4_f32 v[84:87], v43, v43, v[84:87]
	v_mfma_f32_16x16x4_f32 v[80:83], v44, v44, v[80:83]
	v_mfma_f32_16x16x4_f32 v[84:87], v45, v45, v[84:87]
	v_mfma_f32_16x16x4_f32 v[80:83], v46, v46, v[80:83]
	v_mfma_f32_16x16x4_f32 v[84:87], v47, v47, v[84:87]
	v_mfma_f32_16x16x4_f32 v[80:83], v48, v48, v[80:83]
	v_mfma_f32_16x16x4_f32 v[84:87], v49, v49, v[84:87]
	v_mfma_f32_16x16x4_f32 v[80:83], v50, v50, v[80:83]
	v_mfma_f32_16x16x4_f32 v[84:87], v51, v51, v[84:87]
	v_mfma_f32_16x16x4_f32 v[80:83], v52, v52, v[80:83]
	v_mfma_f32_16x16x4_f32 v[84:87], v53, v53, v[84:87]
	v_mfma_f32_16x16x4_f32 v[80:83], v54, v54, v[80:83]
	v_mfma_f32_16x16x4_f32 v[84:87], v55, v55, v[84:87]
	v_mfma_f32_16x16x4_f32 v[80:83], v56, v56, v[80:83]
	v_mfma_f32_16x16x4_f32 v[84:87], v57, v57, v[84:87]
	v_mfma_f32_16x16x4_f32 v[80:83], v58, v58, v[80:83]
	v_mfma_f32_16x16x4_f32 v[84:87], v59, v59, v[84:87]
	v_mfma_f32_16x16x4_f32 v[80:83], v60, v60, v[80:83]
	v_mfma_f32_16x16x4_f32 v[84:87], v61, v61, v[84:87]
	v_mfma_f32_16x16x4_f32 v[80:83], v62, v62, v[80:83]
	v_mfma_f32_16x16x4_f32 v[84:87], v63, v63, v[84:87]
	s_waitcnt vmcnt(0)
; __device__ __forceinline__ void gdn_item(const Params& p, int item, float* sm) {
;     ...
;       for (int t = 0; t < TC; t++) {
;         const float4 k0 = *(const float4*)(bk + t * 128 + sub * 4);
;         const float4 k1 = *(const float4*)(bk + t * 128 + 64 + sub * 4);
;         const float4 q0 = *(const float4*)(bq + t * 128 + sub * 4);
;         const float4 q1 = *(const float4*)(bq + t * 128 + 64 + sub * 4);
;         const float v = bv[t * 16 + cw];
;         const float g = bg[t], be = bg[TC + t];
;         const float qk = bo[TC * 16 + t];
;         float pa = k0.x * S[0] + k0.y * S[1];
;         float pb2 = k0.z * S[2] + k0.w * S[3];
;         float qa = q0.x * S[0] + q0.y * S[1];
;         float qb2 = q0.z * S[2] + q0.w * S[3];
;         pa += k1.x * S[4] + k1.y * S[5];
;         pb2 += k1.z * S[6] + k1.w * S[7];
;         qa += q1.x * S[4] + q1.y * S[5];
;         qb2 += q1.z * S[6] + q1.w * S[7];
;         const float ks = dpp_sum16(pa + pb2);
;         const float qs = dpp_sum16(qa + qb2);
;         const float coef = be * (v - g * ks);
;         const float oo = g * qs + coef * qk;
;         S[0] = g * S[0] + coef * k0.x; S[1] = g * S[1] + coef * k0.y; S[2] = g * S[2] + coef * k0.z; S[3] = g * S[3] + coef * k0.w;
;         S[4] = g * S[4] + coef * k1.x; S[5] = g * S[5] + coef * k1.y; S[6] = g * S[6] + coef * k1.z; S[7] = g * S[7] + coef * k1.w;
;         oreg[t] = oo * 0.08838834764831845f;
	v_lshlrev_b32_e32 v166, 16, v226
	v_and_b32_e32 v167, 0xffff0000, v226
	v_lshlrev_b32_e32 v168, 16, v227
	v_and_b32_e32 v169, 0xffff0000, v227
	v_lshlrev_b32_e32 v170, 16, v228
	v_and_b32_e32 v171, 0xffff0000, v228
	v_lshlrev_b32_e32 v172, 16, v229
	v_and_b32_e32 v173, 0xffff0000, v229
	v_lshlrev_b32_e32 v174, 16, v230
	v_and_b32_e32 v175, 0xffff0000, v230
	v_lshlrev_b32_e32 v176, 16, v231
	v_and_b32_e32 v177, 0xffff0000, v231
	v_lshlrev_b32_e32 v178, 16, v232
	v_and_b32_e32 v179, 0xffff0000, v232
	v_lshlrev_b32_e32 v180, 16, v233
	v_and_b32_e32 v181, 0xffff0000, v233
	v_lshlrev_b32_e32 v182, 16, v234
	v_and_b32_e32 v183, 0xffff0000, v234
	v_lshlrev_b32_e32 v184, 16, v235
	v_and_b32_e32 v185, 0xffff0000, v235
	v_lshlrev_b32_e32 v186, 16, v236
	v_and_b32_e32 v187, 0xffff0000, v236
	v_lshlrev_b32_e32 v188, 16, v237
	v_and_b32_e32 v189, 0xffff0000, v237
	v_lshlrev_b32_e32 v190, 16, v238
	v_and_b32_e32 v191, 0xffff0000, v238
	v_lshlrev_b32_e32 v192, 16, v239
	v_and_b32_e32 v193, 0xffff0000, v239
	v_lshlrev_b32_e32 v194, 16, v240
	v_and_b32_e32 v195, 0xffff0000, v240
	v_lshlrev_b32_e32 v196, 16, v241
	v_and_b32_e32 v197, 0xffff0000, v241
	s_nop 0
	v_mfma_f32_16x16x4_f32 v[198:201], v166, v32, 0
	v_mfma_f32_16x16x4_f32 v[202:205], v167, v33, 0
	v_mfma_f32_16x16x4_f32 v[198:201], v168, v34, v[198:201]
	v_mfma_f32_16x16x4_f32 v[202:205], v169, v35, v[202:205]
	v_mfma_f32_16x16x4_f32 v[198:201], v170, v36, v[198:201]
	v_mfma_f32_16x16x4_f32 v[202:205], v171, v37, v[202:205]
	v_mfma_f32_16x16x4_f32 v[198:201], v172, v38, v[198:201]
	v_mfma_f32_16x16x4_f32 v[202:205], v173, v39, v[202:205]
	v_mfma_f32_16x16x4_f32 v[198:201], v174, v40, v[198:201]
	v_mfma_f32_16x16x4_f32 v[202:205], v175, v41, v[202:205]
	v_mfma_f32_16x16x4_f32 v[198:201], v176, v42, v[198:201]
	v_mfma_f32_16x16x4_f32 v[202:205], v177, v43, v[202:205]
	v_mfma_f32_16x16x4_f32 v[198:201], v178, v44, v[198:201]
	v_mfma_f32_16x16x4_f32 v[202:205], v179, v45, v[202:205]
	v_mfma_f32_16x16x4_f32 v[198:201], v180, v46, v[198:201]
	v_mfma_f32_16x16x4_f32 v[202:205], v181, v47, v[202:205]
	v_mfma_f32_16x16x4_f32 v[198:201], v182, v48, v[198:201]
	v_mfma_f32_16x16x4_f32 v[202:205], v183, v49, v[202:205]
	v_mfma_f32_16x16x4_f32 v[198:201], v184, v50, v[198:201]
	v_mfma_f32_16x16x4_f32 v[202:205], v185, v51, v[202:205]
	v_mfma_f32_16x16x4_f32 v[198:201], v186, v52, v[198:201]
	v_mfma_f32_16x16x4_f32 v[202:205], v187, v53, v[202:205]
	v_mfma_f32_16x16x4_f32 v[198:201], v188, v54, v[198:201]
	v_mfma_f32_16x16x4_f32 v[202:205], v189, v55, v[202:205]
	v_mfma_f32_16x16x4_f32 v[198:201], v190, v56, v[198:201]
	v_mfma_f32_16x16x4_f32 v[202:205], v191, v57, v[202:205]
	v_mfma_f32_16x16x4_f32 v[198:201], v192, v58, v[198:201]
	v_mfma_f32_16x16x4_f32 v[202:205], v193, v59, v[202:205]
	v_mfma_f32_16x16x4_f32 v[198:201], v194, v60, v[198:201]
	v_mfma_f32_16x16x4_f32 v[202:205], v195, v61, v[202:205]
	v_mfma_f32_16x16x4_f32 v[198:201], v196, v62, v[198:201]
	v_mfma_f32_16x16x4_f32 v[202:205], v197, v63, v[202:205]
	v_mov_b32_e32 v157, s12
	s_waitcnt lgkmcnt(0)
	ds_read_b128 v[88:91], v157 offset:1024
	ds_read_b128 v[92:95], v157 offset:1040
	ds_read_b128 v[96:99], v157 offset:1056
	ds_read_b128 v[100:103], v157 offset:1072
	v_add_f32_e32 v80, v80, v84
	v_add_f32_e32 v81, v81, v85
	v_add_f32_e32 v82, v82, v86
	v_add_f32_e32 v83, v83, v87
	ds_write_b128 v155, v[80:83]
	s_waitcnt lgkmcnt(0)
	ds_read_b128 v[136:139], v157 offset:64
	s_lshl_b32 s13, s2, 10
	s_add_i32 s18, s13, 0xac40000
	v_add_u32_e32 v156, s18, v242
	v_add_f32_e32 v198, v198, v202
	v_add_f32_e32 v199, v199, v203
	v_add_f32_e32 v200, v200, v204
	v_add_f32_e32 v201, v201, v205
	v_add_u32_e32 v159, 0, v160
	v_cmp_le_u32_e32 vcc, v152, v159
	s_nop 1
	v_cndmask_b32_e64 v198, 0, v198, vcc
	v_add_u32_e32 v159, 1, v160
	v_cmp_le_u32_e32 vcc, v152, v159
	s_nop 1
	v_cndmask_b32_e64 v199, 0, v199, vcc
	v_add_u32_e32 v159, 2, v160
	v_cmp_le_u32_e32 vcc, v152, v159
	s_nop 1
	v_cndmask_b32_e64 v200, 0, v200, vcc
	v_add_u32_e32 v159, 3, v160
	v_cmp_le_u32_e32 vcc, v152, v159
	s_nop 1
	v_cndmask_b32_e64 v201, 0, v201, vcc
	s_nop 0
	global_store_dword v156, v198, s[6:7]
	global_store_dword v156, v199, s[6:7] offset:64
	global_store_dword v156, v200, s[6:7] offset:128
	global_store_dword v156, v201, s[6:7] offset:192
	v_cmp_eq_u32_e32 vcc, 0, v152
	s_nop 1
	v_cndmask_b32_e64 v159, 0, 1.0, vcc
	v_mul_f32_e32 v104, v88, v159
	ds_read_b128 v[120:123], v157 offset:128
	v_cmp_eq_u32_e32 vcc, 1, v152
	s_waitcnt lgkmcnt(1)
	s_nop 0
	v_cndmask_b32_e64 v159, 0, 1.0, vcc
	v_fma_f32 v159, -v136, v104, v159
	v_mul_f32_e32 v105, v89, v159
	ds_read_b128 v[136:139], v157 offset:192
	v_cmp_eq_u32_e32 vcc, 2, v152
	s_waitcnt lgkmcnt(1)
	s_nop 0
	v_cndmask_b32_e64 v159, 0, 1.0, vcc
	v_fma_f32 v159, -v120, v104, v159
	v_fma_f32 v159, -v121, v105, v159
	v_mul_f32_e32 v106, v90, v159
	ds_read_b128 v[120:123], v157 offset:256
	v_cmp_eq_u32_e32 vcc, 3, v152
	s_waitcnt lgkmcnt(1)
	s_nop 0
	v_cndmask_b32_e64 v159, 0, 1.0, vcc
	v_fma_f32 v159, -v136, v104, v159
	v_fma_f32 v159, -v137, v105, v159
	v_fma_f32 v159, -v138, v106, v159
	v_mul_f32_e32 v107, v91, v159
	ds_read_b128 v[136:139], v157 offset:320
	ds_read_b128 v[140:143], v157 offset:336
	v_cmp_eq_u32_e32 vcc, 4, v152
	s_waitcnt lgkmcnt(2)
	s_nop 0
	v_cndmask_b32_e64 v159, 0, 1.0, vcc
	v_fma_f32 v159, -v120, v104, v159
	v_fma_f32 v159, -v121, v105, v159
	v_fma_f32 v159, -v122, v106, v159
	v_fma_f32 v159, -v123, v107, v159
	v_mul_f32_e32 v108, v92, v159
	ds_read_b128 v[120:123], v157 offset:384
	ds_read_b128 v[124:127], v157 offset:400
	v_cmp_eq_u32_e32 vcc, 5, v152
	s_waitcnt lgkmcnt(2)
; __device__ __forceinline__ void gdn_item(const Params& p, int item, float* sm) {
;     ...
;         const float ks = dpp_sum16(pa + pb2);
;         const float qs = dpp_sum16(qa + qb2);
;         const float coef = be * (v - g * ks);
;         const float oo = g * qs + coef * qk;
;         S[0] = g * S[0] + coef * k0.x; S[1] = g * S[1] + coef * k0.y; S[2] = g * S[2] + coef * k0.z; S[3] = g * S[3] + coef * k0.w;
;         S[4] = g * S[4] + coef * k1.x; S[5] = g * S[5] + coef * k1.y; S[6] = g * S[6] + coef * k1.z; S[7] = g * S[7] + coef * k1.w;
	s_nop 0
	v_cndmask_b32_e64 v159, 0, 1.0, vcc
	v_fma_f32 v159, -v136, v104, v159
	v_fma_f32 v159, -v137, v105, v159
	v_fma_f32 v159, -v138, v106, v159
	v_fma_f32 v159, -v139, v107, v159
	v_fma_f32 v159, -v140, v108, v159
	v_mul_f32_e32 v109, v93, v159
	ds_read_b128 v[136:139], v157 offset:448
	ds_read_b128 v[140:143], v157 offset:464
	v_cmp_eq_u32_e32 vcc, 6, v152
	s_waitcnt lgkmcnt(2)
	s_nop 0
	v_cndmask_b32_e64 v159, 0, 1.0, vcc
	v_fma_f32 v159, -v120, v104, v159
	v_fma_f32 v159, -v121, v105, v159
	v_fma_f32 v159, -v122, v106, v159
	v_fma_f32 v159, -v123, v107, v159
	v_fma_f32 v159, -v124, v108, v159
	v_fma_f32 v159, -v125, v109, v159
	v_mul_f32_e32 v110, v94, v159
	ds_read_b128 v[120:123], v157 offset:512
	ds_read_b128 v[124:127], v157 offset:528
	v_cmp_eq_u32_e32 vcc, 7, v152
	s_waitcnt lgkmcnt(2)
	s_nop 0
	v_cndmask_b32_e64 v159, 0, 1.0, vcc
	v_fma_f32 v159, -v136, v104, v159
	v_fma_f32 v159, -v137, v105, v159
	v_fma_f32 v159, -v138, v106, v159
	v_fma_f32 v159, -v139, v107, v159
	v_fma_f32 v159, -v140, v108, v159
	v_fma_f32 v159, -v141, v109, v159
	v_fma_f32 v159, -v142, v110, v159
	v_mul_f32_e32 v111, v95, v159
	ds_read_b128 v[136:139], v157 offset:576
	ds_read_b128 v[140:143], v157 offset:592
	ds_read_b128 v[144:147], v157 offset:608
	v_cmp_eq_u32_e32 vcc, 8, v152
	s_waitcnt lgkmcnt(3)
	s_nop 0
	v_cndmask_b32_e64 v159, 0, 1.0, vcc
	v_fma_f32 v159, -v120, v104, v159
	v_fma_f32 v159, -v121, v105, v159
	v_fma_f32 v159, -v122, v106, v159
	v_fma_f32 v159, -v123, v107, v159
	v_fma_f32 v159, -v124, v108, v159
	v_fma_f32 v159, -v125, v109, v159
	v_fma_f32 v159, -v126, v110, v159
	v_fma_f32 v159, -v127, v111, v159
	v_mul_f32_e32 v112, v96, v159
	ds_read_b128 v[120:123], v157 offset:640
	ds_read_b128 v[124:127], v157 offset:656
	ds_read_b128 v[128:131], v157 offset:672
	v_cmp_eq_u32_e32 vcc, 9, v152
	s_waitcnt lgkmcnt(3)
	s_nop 0
	v_cndmask_b32_e64 v159, 0, 1.0, vcc
	v_fma_f32 v159, -v136, v104, v159
	v_fma_f32 v159, -v137, v105, v159
	v_fma_f32 v159, -v138, v106, v159
	v_fma_f32 v159, -v139, v107, v159
	v_fma_f32 v159, -v140, v108, v159
	v_fma_f32 v159, -v141, v109, v159
	v_fma_f32 v159, -v142, v110, v159
	v_fma_f32 v159, -v143, v111, v159
	v_fma_f32 v159, -v144, v112, v159
	v_mul_f32_e32 v113, v97, v159
	ds_read_b128 v[136:139], v157 offset:704
	ds_read_b128 v[140:143], v157 offset:720
	ds_read_b128 v[144:147], v157 offset:736
	v_cmp_eq_u32_e32 vcc, 10, v152
	s_waitcnt lgkmcnt(3)
	s_nop 0
	v_cndmask_b32_e64 v159, 0, 1.0, vcc
	v_fma_f32 v159, -v120, v104, v159
	v_fma_f32 v159, -v121, v105, v159
	v_fma_f32 v159, -v122, v106, v159
	v_fma_f32 v159, -v123, v107, v159
	v_fma_f32 v159, -v124, v108, v159
	v_fma_f32 v159, -v125, v109, v159
	v_fma_f32 v159, -v126, v110, v159
	v_fma_f32 v159, -v127, v111, v159
	v_fma_f32 v159, -v128, v112, v159
	v_fma_f32 v159, -v129, v113, v159
	v_mul_f32_e32 v114, v98, v159
	ds_read_b128 v[120:123], v157 offset:768
	ds_read_b128 v[124:127], v157 offset:784
	ds_read_b128 v[128:131], v157 offset:800
	v_cmp_eq_u32_e32 vcc, 11, v152
	s_waitcnt lgkmcnt(3)
	s_nop 0
	v_cndmask_b32_e64 v159, 0, 1.0, vcc
	v_fma_f32 v159, -v136, v104, v159
	v_fma_f32 v159, -v137, v105, v159
	v_fma_f32 v159, -v138, v106, v159
	v_fma_f32 v159, -v139, v107, v159
	v_fma_f32 v159, -v140, v108, v159
	v_fma_f32 v159, -v141, v109, v159
	v_fma_f32 v159, -v142, v110, v159
	v_fma_f32 v159, -v143, v111, v159
	v_fma_f32 v159, -v144, v112, v159
	v_fma_f32 v159, -v145, v113, v159
	v_fma_f32 v159, -v146, v114, v159
	v_mul_f32_e32 v115, v99, v159
	ds_read_b128 v[136:139], v157 offset:832
	ds_read_b128 v[140:143], v157 offset:848
	ds_read_b128 v[144:147], v157 offset:864
	ds_read_b128 v[148:151], v157 offset:880
	v_cmp_eq_u32_e32 vcc, 12, v152
	s_waitcnt lgkmcnt(4)
; __device__ __forceinline__ void gdn_item(const Params& p, int item, float* sm) {
;     ...
;         const float ks = dpp_sum16(pa + pb2);
;         const float qs = dpp_sum16(qa + qb2);
;         const float coef = be * (v - g * ks);
;         const float oo = g * qs + coef * qk;
;         S[0] = g * S[0] + coef * k0.x; S[1] = g * S[1] + coef * k0.y; S[2] = g * S[2] + coef * k0.z; S[3] = g * S[3] + coef * k0.w;
;         S[4] = g * S[4] + coef * k1.x; S[5] = g * S[5] + coef * k1.y; S[6] = g * S[6] + coef * k1.z; S[7] = g * S[7] + coef * k1.w;
	s_nop 0
	v_cndmask_b32_e64 v159, 0, 1.0, vcc
	v_fma_f32 v159, -v120, v104, v159
	v_fma_f32 v159, -v121, v105, v159
	v_fma_f32 v159, -v122, v106, v159
	v_fma_f32 v159, -v123, v107, v159
	v_fma_f32 v159, -v124, v108, v159
	v_fma_f32 v159, -v125, v109, v159
	v_fma_f32 v159, -v126, v110, v159
	v_fma_f32 v159, -v127, v111, v159
	v_fma_f32 v159, -v128, v112, v159
	v_fma_f32 v159, -v129, v113, v159
	v_fma_f32 v159, -v130, v114, v159
	v_fma_f32 v159, -v131, v115, v159
	v_mul_f32_e32 v116, v100, v159
	ds_read_b128 v[120:123], v157 offset:896
	ds_read_b128 v[124:127], v157 offset:912
	ds_read_b128 v[128:131], v157 offset:928
	ds_read_b128 v[132:135], v157 offset:944
	v_cmp_eq_u32_e32 vcc, 13, v152
	s_waitcnt lgkmcnt(4)
	s_nop 0
	v_cndmask_b32_e64 v159, 0, 1.0, vcc
	v_fma_f32 v159, -v136, v104, v159
	v_fma_f32 v159, -v137, v105, v159
	v_fma_f32 v159, -v138, v106, v159
	v_fma_f32 v159, -v139, v107, v159
	v_fma_f32 v159, -v140, v108, v159
	v_fma_f32 v159, -v141, v109, v159
	v_fma_f32 v159, -v142, v110, v159
	v_fma_f32 v159, -v143, v111, v159
	v_fma_f32 v159, -v144, v112, v159
	v_fma_f32 v159, -v145, v113, v159
	v_fma_f32 v159, -v146, v114, v159
	v_fma_f32 v159, -v147, v115, v159
	v_fma_f32 v159, -v148, v116, v159
	v_mul_f32_e32 v117, v101, v159
	ds_read_b128 v[136:139], v157 offset:960
	ds_read_b128 v[140:143], v157 offset:976
	ds_read_b128 v[144:147], v157 offset:992
	ds_read_b128 v[148:151], v157 offset:1008
	v_cmp_eq_u32_e32 vcc, 14, v152
	s_waitcnt lgkmcnt(4)
	s_nop 0
	v_cndmask_b32_e64 v159, 0, 1.0, vcc
	v_fma_f32 v159, -v120, v104, v159
	v_fma_f32 v159, -v121, v105, v159
	v_fma_f32 v159, -v122, v106, v159
	v_fma_f32 v159, -v123, v107, v159
	v_fma_f32 v159, -v124, v108, v159
	v_fma_f32 v159, -v125, v109, v159
	v_fma_f32 v159, -v126, v110, v159
	v_fma_f32 v159, -v127, v111, v159
	v_fma_f32 v159, -v128, v112, v159
	v_fma_f32 v159, -v129, v113, v159
	v_fma_f32 v159, -v130, v114, v159
	v_fma_f32 v159, -v131, v115, v159
	v_fma_f32 v159, -v132, v116, v159
	v_fma_f32 v159, -v133, v117, v159
	v_mul_f32_e32 v118, v102, v159
	v_cmp_eq_u32_e32 vcc, 15, v152
	s_waitcnt lgkmcnt(0)
	s_nop 0
	v_cndmask_b32_e64 v159, 0, 1.0, vcc
	v_fma_f32 v159, -v136, v104, v159
	v_fma_f32 v159, -v137, v105, v159
	v_fma_f32 v159, -v138, v106, v159
	v_fma_f32 v159, -v139, v107, v159
	v_fma_f32 v159, -v140, v108, v159
	v_fma_f32 v159, -v141, v109, v159
	v_fma_f32 v159, -v142, v110, v159
	v_fma_f32 v159, -v143, v111, v159
	v_fma_f32 v159, -v144, v112, v159
	v_fma_f32 v159, -v145, v113, v159
	v_fma_f32 v159, -v146, v114, v159
	v_fma_f32 v159, -v147, v115, v159
	v_fma_f32 v159, -v148, v116, v159
	v_fma_f32 v159, -v149, v117, v159
	v_fma_f32 v159, -v150, v118, v159
	v_mul_f32_e32 v119, v103, v159
	v_lshl_add_u32 v156, v152, 2, s13
	global_store_dword v156, v104, s[8:9]
	global_store_dword v156, v105, s[8:9] offset:64
	global_store_dword v156, v106, s[8:9] offset:128
	global_store_dword v156, v107, s[8:9] offset:192
	global_store_dword v156, v108, s[8:9] offset:256
	global_store_dword v156, v109, s[8:9] offset:320
	global_store_dword v156, v110, s[8:9] offset:384
	global_store_dword v156, v111, s[8:9] offset:448
	global_store_dword v156, v112, s[8:9] offset:512
	global_store_dword v156, v113, s[8:9] offset:576
	global_store_dword v156, v114, s[8:9] offset:640
	global_store_dword v156, v115, s[8:9] offset:704
	global_store_dword v156, v116, s[8:9] offset:768
	global_store_dword v156, v117, s[8:9] offset:832
	global_store_dword v156, v118, s[8:9] offset:896
	global_store_dword v156, v119, s[8:9] offset:960
	s_add_i32 s2, s2, s11
	s_branch .Lmv_item
